# attention: skip the window-mask code on steps whose keys are all inside the window (exact)
# speedup vs baseline: 1.0092x; 1.0027x over previous
.Lmsk_chk:
	s_add_i32 s100, s53, -1
	s_lshr_b32 s100, s100, 1
	s_and_b32 s101, s46, 1
	s_cmp_lg_u32 s100, s101
	s_cbranch_scc1 .LBB0_792
	s_mul_i32 s30, s54, 0xffffffd0
	v_mov_b32_e32 v38, s4
	v_cmp_lt_i32_e64 s[30:31], s30, v34
	s_mul_i32 s10, s54, 3
	s_mul_i32 s16, s54, -15
	v_cndmask_b32_e64 v152, v152, v38, s[30:31]
	s_mul_i32 s30, s54, 0xffffffd1
	v_cmp_ge_i32_e64 s[30:31], s30, v34
	s_mul_i32 s18, s54, -14
	s_mul_i32 s20, s54, -13
	v_cndmask_b32_e64 v153, v241, v153, s[30:31]
	s_mul_i32 s30, s54, 0xffffffd2
	v_cmp_ge_i32_e64 s[30:31], s30, v34
	s_mul_i32 s24, s54, 0xffffffe1
	s_mul_i32 s26, s54, 0xffffffe2
	v_cndmask_b32_e64 v154, v241, v154, s[30:31]
	s_mul_i32 s30, s54, 0xffffffd3
	v_cmp_ge_i32_e64 s[30:31], s30, v34
	s_mul_i32 s28, s54, 0xffffffe3
	v_cmp_lt_i32_e32 vcc, 0, v34
	v_cndmask_b32_e64 v155, v241, v155, s[30:31]
	v_cmp_lt_i32_e64 s[30:31], s84, v34
	v_cmp_lt_i32_e64 s[6:7], s54, v34
	v_cmp_lt_i32_e64 s[8:9], s55, v34
	v_cndmask_b32_e64 v196, v196, v38, s[30:31]
	s_mul_i32 s30, s54, 17
	v_cmp_ge_i32_e64 s[30:31], s30, v34
	v_cmp_lt_i32_e64 s[10:11], s10, v34
	v_cmp_lt_i32_e64 s[12:13], s85, v34
	v_cndmask_b32_e64 v197, v241, v197, s[30:31]
	s_mul_i32 s30, s54, 18
	v_cmp_ge_i32_e64 s[30:31], s30, v34
	v_cmp_lt_i32_e64 s[16:17], s16, v34
	v_cmp_lt_i32_e64 s[18:19], s18, v34
	v_cndmask_b32_e64 v198, v241, v198, s[30:31]
	s_mul_i32 s30, s54, 19
	v_cmp_lt_i32_e64 s[20:21], s20, v34
	v_cmp_lt_i32_e64 s[22:23], s0, v34
	v_cmp_lt_i32_e64 s[24:25], s24, v34
	v_cmp_lt_i32_e64 s[26:27], s26, v34
	v_cmp_lt_i32_e64 s[28:29], s28, v34
	v_cmp_ge_i32_e64 s[30:31], s30, v34
	v_cndmask_b32_e32 v192, v192, v38, vcc
	v_cndmask_b32_e64 v193, v193, v241, s[6:7]
	v_cndmask_b32_e64 v194, v194, v241, s[8:9]
	v_cndmask_b32_e64 v195, v195, v241, s[10:11]
	v_cndmask_b32_e64 v180, v180, v38, s[12:13]
	v_cndmask_b32_e64 v181, v181, v241, s[16:17]
	v_cndmask_b32_e64 v182, v182, v241, s[18:19]
	v_cndmask_b32_e64 v183, v183, v241, s[20:21]
	v_cndmask_b32_e64 v156, v156, v38, s[22:23]
	v_cndmask_b32_e64 v157, v157, v241, s[24:25]
	v_cndmask_b32_e64 v158, v158, v241, s[26:27]
	v_cndmask_b32_e64 v159, v159, v241, s[28:29]
	v_cndmask_b32_e64 v199, v241, v199, s[30:31]
	v_cndmask_b32_e32 v188, v188, v38, vcc
	v_cndmask_b32_e64 v189, v189, v241, s[6:7]
	v_cndmask_b32_e64 v190, v190, v241, s[8:9]
	v_cndmask_b32_e64 v191, v191, v241, s[10:11]
	v_cndmask_b32_e64 v184, v184, v38, s[12:13]
	v_cndmask_b32_e64 v185, v185, v241, s[16:17]
	v_cndmask_b32_e64 v186, v186, v241, s[18:19]
	v_cndmask_b32_e64 v187, v187, v241, s[20:21]
	v_cndmask_b32_e64 v172, v172, v38, s[22:23]
	v_cndmask_b32_e64 v173, v173, v241, s[24:25]
	v_cndmask_b32_e64 v174, v174, v241, s[26:27]
	v_cndmask_b32_e64 v175, v175, v241, s[28:29]
